# DA half prologue: the four q pieces and the first K/V tile rows are loaded together with counted waits instead of six serialized round trips
# speedup vs baseline: 1.0001x; 1.0001x over previous
; #define TL_BEGIN(Kg, kpitch, Vg, vpitch, t0, t1) do { TL_FETCH(Kg, kpitch, Vg, vpitch, t0); TL_WRITE(0); __syncthreads(); if ((t0) + 1 < (t1)) TL_FETCH(Kg, kpitch, Vg, vpitch, (t0) + 1); } while (0)
; __device__ __forceinline__ bf16x8 scale_frag(bf16x8 q, float c) { float v[8]; unpack8(__builtin_bit_cast(u32x4, q), v); return pack8(v[0] * c, v[1] * c, v[2] * c, v[3] * c, v[4] * c, v[5] * c, v[6] * c, v[7] * c); }
; __device__ __forceinline__ void phase_da(const Params& p, int layer, LAS unsigned char* lds, const bf16_t* Z, bf16_t* Mixed, int tid, int wid, int lane) {
;     ...
;             const int qb = half ? 63 - qa : qa;
;             const int q0w = qb * 256 + 32 * wid, qpos = q0w + r;
;             const size_t row = (size_t)b * SEQ + qpos;
;             bf16x8 qf1[2], qf2[2];
; #pragma unroll
;             for (int ks = 0; ks < 2; ++ks) { qf1[ks] = scale_frag(*(const bf16x8*)(Z + row * ZLD + C_DAQ + hd * 64 + 16 * ks + 8 * h), c); qf2[ks] = scale_frag(*(const bf16x8*)(Z + row * ZLD + C_DAQ + hd * 64 + 32 + 16 * ks + 8 * h), c); }
;             float m1 = NEG, l1 = 0.f, m2 = NEG, l2 = 0.f; f32x16 oa0, oa1, ob0, ob1;
; #pragma unroll
;             for (int i = 0; i < 16; ++i) { oa0[i] = 0.f; oa1[i] = 0.f; ob0[i] = 0.f; ob1[i] = 0.f; }
;             const int ntile = 4 * (qb + 1);
;             f32x16 L1, L2;
;             TL_BEGIN(Kg, ZLD, Vg, ZLD, 0, ntile);
.LBB0_234:
	s_and_b64 s[2:3], s[6:7], exec
	s_cselect_b32 s19, s15, s16
	s_lshl_b32 s18, s19, 8
	s_add_i32 s17, s18, s12
	v_or_b32_e32 v230, s17, v246
	v_ashrrev_i32_e32 v231, 31, v230
	v_lshl_add_u64 v[228:229], s[4:5], 0, v[230:231]
	v_mad_u64_u32 v[38:39], s[2:3], v228, s59, v[222:223]
	v_mad_i32_i24 v39, v229, s59, v39
	global_load_dwordx4 v[34:37], v[38:39], off offset:2048
	global_load_dwordx4 v[50:53], v[38:39], off offset:2112
	global_load_dwordx4 v[54:57], v[38:39], off offset:2080
	global_load_dwordx4 v[58:61], v[38:39], off offset:2144
	global_load_dwordx4 v[62:65], v[208:209], off offset:2560
	global_load_dwordx4 v[66:69], v[210:211], off offset:3072
	s_cmp_lt_i32 s17, 0
	s_waitcnt vmcnt(5)
	v_lshlrev_b32_e32 v40, 16, v34
	v_and_b32_e32 v41, 0xffff0000, v34
	v_lshlrev_b32_e32 v34, 16, v35
	v_and_b32_e32 v35, 0xffff0000, v35
	v_lshlrev_b32_e32 v42, 16, v36
	v_and_b32_e32 v43, 0xffff0000, v36
	v_lshlrev_b32_e32 v36, 16, v37
	v_and_b32_e32 v37, 0xffff0000, v37
	v_pk_mul_f32 v[34:35], v[34:35], s[54:55] op_sel_hi:[1,0]
	v_pk_mul_f32 v[36:37], v[36:37], s[54:55] op_sel_hi:[1,0]
	v_cvt_pk_bf16_f32 v153, v34, v35
	v_cvt_pk_bf16_f32 v155, v36, v37
	v_pk_mul_f32 v[40:41], v[40:41], s[54:55] op_sel_hi:[1,0]
	v_pk_mul_f32 v[42:43], v[42:43], s[54:55] op_sel_hi:[1,0]
	v_cvt_pk_bf16_f32 v152, v40, v41
	v_cvt_pk_bf16_f32 v154, v42, v43
	s_waitcnt vmcnt(4)
	v_mov_b32_e32 v34, v50
	v_mov_b32_e32 v35, v51
	v_mov_b32_e32 v36, v52
	v_mov_b32_e32 v37, v53
	v_lshlrev_b32_e32 v40, 16, v34
	v_and_b32_e32 v41, 0xffff0000, v34
	v_lshlrev_b32_e32 v34, 16, v35
	v_and_b32_e32 v35, 0xffff0000, v35
	v_lshlrev_b32_e32 v42, 16, v36
	v_and_b32_e32 v43, 0xffff0000, v36
	v_lshlrev_b32_e32 v36, 16, v37
	v_and_b32_e32 v37, 0xffff0000, v37
	v_pk_mul_f32 v[34:35], v[34:35], s[54:55] op_sel_hi:[1,0]
	v_pk_mul_f32 v[36:37], v[36:37], s[54:55] op_sel_hi:[1,0]
	v_cvt_pk_bf16_f32 v161, v34, v35
	v_cvt_pk_bf16_f32 v163, v36, v37
	v_pk_mul_f32 v[40:41], v[40:41], s[54:55] op_sel_hi:[1,0]
	v_pk_mul_f32 v[42:43], v[42:43], s[54:55] op_sel_hi:[1,0]
	v_cvt_pk_bf16_f32 v160, v40, v41
	v_cvt_pk_bf16_f32 v162, v42, v43
	s_waitcnt vmcnt(3)
	v_mov_b32_e32 v34, v54
	v_mov_b32_e32 v35, v55
	v_mov_b32_e32 v36, v56
	v_mov_b32_e32 v37, v57
	v_lshlrev_b32_e32 v40, 16, v34
	v_and_b32_e32 v41, 0xffff0000, v34
	v_lshlrev_b32_e32 v34, 16, v35
	v_and_b32_e32 v35, 0xffff0000, v35
	v_lshlrev_b32_e32 v42, 16, v36
	v_and_b32_e32 v43, 0xffff0000, v36
	v_lshlrev_b32_e32 v36, 16, v37
	v_and_b32_e32 v37, 0xffff0000, v37
	v_pk_mul_f32 v[34:35], v[34:35], s[54:55] op_sel_hi:[1,0]
	v_pk_mul_f32 v[36:37], v[36:37], s[54:55] op_sel_hi:[1,0]
	v_cvt_pk_bf16_f32 v157, v34, v35
	v_cvt_pk_bf16_f32 v159, v36, v37
	v_pk_mul_f32 v[40:41], v[40:41], s[54:55] op_sel_hi:[1,0]
	v_pk_mul_f32 v[42:43], v[42:43], s[54:55] op_sel_hi:[1,0]
	v_cvt_pk_bf16_f32 v156, v40, v41
	v_cvt_pk_bf16_f32 v158, v42, v43
	s_waitcnt vmcnt(2)
	v_mov_b32_e32 v34, v58
	v_mov_b32_e32 v35, v59
	v_mov_b32_e32 v36, v60
	v_mov_b32_e32 v37, v61
	v_lshlrev_b32_e32 v38, 16, v34
	v_and_b32_e32 v39, 0xffff0000, v34
	v_lshlrev_b32_e32 v34, 16, v35
	v_and_b32_e32 v35, 0xffff0000, v35
	v_lshlrev_b32_e32 v40, 16, v36
	v_and_b32_e32 v41, 0xffff0000, v36
	v_lshlrev_b32_e32 v36, 16, v37
	v_and_b32_e32 v37, 0xffff0000, v37
	v_pk_mul_f32 v[34:35], v[34:35], s[54:55] op_sel_hi:[1,0]
	v_pk_mul_f32 v[36:37], v[36:37], s[54:55] op_sel_hi:[1,0]
	v_cvt_pk_bf16_f32 v149, v34, v35
	v_cvt_pk_bf16_f32 v151, v36, v37
	v_pk_mul_f32 v[38:39], v[38:39], s[54:55] op_sel_hi:[1,0]
	v_pk_mul_f32 v[40:41], v[40:41], s[54:55] op_sel_hi:[1,0]
	v_cvt_pk_bf16_f32 v148, v38, v39
	v_cvt_pk_bf16_f32 v150, v40, v41
	s_waitcnt vmcnt(1)
	ds_write_b128 v250, v[62:65]
	s_waitcnt vmcnt(0)
	v_mov_b32_e32 v34, v66
	v_mov_b32_e32 v35, v67
	v_mov_b32_e32 v36, v68
	v_mov_b32_e32 v37, v69
	ds_write_b16 v252, v34 offset:9216
	ds_write_b16_d16_hi v252, v34 offset:9360
	ds_write_b16 v252, v35 offset:9504
	ds_write_b16_d16_hi v252, v35 offset:9648
	ds_write_b16 v252, v36 offset:9792
	ds_write_b16_d16_hi v252, v36 offset:9936
	ds_write_b16 v252, v37 offset:10080
	ds_write_b16_d16_hi v175, v37 offset:9216
	s_waitcnt lgkmcnt(0)
	s_barrier
; #define LAS __attribute__((address_space(3)))
; __device__ __forceinline__ int rowi32(int i, int h) { return (i & 3) + 8 * (i >> 2) + 4 * h; }
; __device__ __forceinline__ void attn_sub_x2(float& m1, float& l1, f32x16& oa0, f32x16& oa1, float& m2, float& l2, f32x16& ob0, f32x16& ob1, ...
;     f32x16 s1 = qk_sub<2>(qf1, Ks, kr0, 0, r, h), s2 = qk_sub<2>(qf2, Ks, kr0, 32, r, h);
;     if (need_mask) {
; #pragma unroll
;         for (int i = 0; i < 16; ++i) { const bool ok = (key0 + rowi32(i, h)) <= qpos; s1[i] = ok ? s1[i] : NEG; s2[i] = ok ? s2[i] : NEG; }
;     }
	global_load_dwordx4 v[130:133], v[212:213], off
	global_load_dwordx4 v[134:137], v[214:215], off offset:2560
	s_cbranch_scc1 .LBB0_239
	v_add_u32_e32 v34, v242, v188
	ds_read_b128 v[2:5], v34
	ds_read_b128 v[18:21], v34 offset:32
	s_cmp_lg_u32 s17, 0
	s_waitcnt lgkmcnt(1)
	v_mfma_f32_32x32x16_bf16 v[2:17], v[2:5], v[152:155], 0
	s_waitcnt lgkmcnt(0)
	v_mfma_f32_32x32x16_bf16 v[2:17], v[18:21], v[156:159], v[2:17]
	ds_read_b128 v[18:21], v34 offset:64
	ds_read_b128 v[34:37], v34 offset:96
	s_waitcnt lgkmcnt(1)
	v_mfma_f32_32x32x16_bf16 v[18:33], v[18:21], v[160:163], 0
	s_waitcnt lgkmcnt(0)
	v_mfma_f32_32x32x16_bf16 v[18:33], v[34:37], v[148:151], v[18:33]
	s_cbranch_scc1 .LBB0_237
	v_cmp_gt_i32_e32 vcc, v186, v230
	v_or_b32_e32 v34, 2, v186
	s_nop 2
	v_cndmask_b32_e32 v2, v2, v180, vcc
	s_nop 4
	v_cndmask_b32_e32 v18, v18, v180, vcc
	v_cmp_lt_i32_e32 vcc, v186, v230
	s_nop 1
	v_cndmask_b32_e32 v3, v180, v3, vcc
	v_cndmask_b32_e32 v19, v180, v19, vcc
	v_cmp_gt_i32_e32 vcc, v34, v230
	v_or_b32_e32 v34, 3, v186
	s_nop 0
	v_cndmask_b32_e32 v4, v4, v180, vcc
	v_cndmask_b32_e32 v20, v20, v180, vcc
	v_cmp_gt_i32_e32 vcc, v34, v230
	v_or_b32_e32 v34, 8, v186
	s_nop 0
	v_cndmask_b32_e32 v5, v5, v180, vcc
	v_cndmask_b32_e32 v21, v21, v180, vcc
	v_cmp_gt_i32_e32 vcc, v34, v230
	v_or_b32_e32 v34, 9, v186
	s_nop 0
	v_cndmask_b32_e32 v6, v6, v180, vcc
	v_cndmask_b32_e32 v22, v22, v180, vcc
	v_cmp_gt_i32_e32 vcc, v34, v230
	v_or_b32_e32 v34, 10, v186
	s_nop 0
	v_cndmask_b32_e32 v7, v7, v180, vcc
	v_cndmask_b32_e32 v23, v23, v180, vcc
	v_cmp_gt_i32_e32 vcc, v34, v230
	v_or_b32_e32 v34, 11, v186
	s_nop 0
	v_cndmask_b32_e32 v8, v8, v180, vcc
	v_cndmask_b32_e32 v24, v24, v180, vcc
	v_cmp_gt_i32_e32 vcc, v34, v230
	v_or_b32_e32 v34, 16, v186
	s_nop 0
	v_cndmask_b32_e32 v9, v9, v180, vcc
	v_cndmask_b32_e32 v25, v25, v180, vcc
	v_cmp_gt_i32_e32 vcc, v34, v230
	v_or_b32_e32 v34, 17, v186
	s_nop 0
	v_cndmask_b32_e32 v10, v10, v180, vcc
	v_cndmask_b32_e32 v26, v26, v180, vcc
	v_cmp_gt_i32_e32 vcc, v34, v230
	v_or_b32_e32 v34, 18, v186
	s_nop 0
	v_cndmask_b32_e32 v11, v11, v180, vcc
	v_cndmask_b32_e32 v27, v27, v180, vcc
	v_cmp_gt_i32_e32 vcc, v34, v230
	v_or_b32_e32 v34, 19, v186
	s_nop 0
	v_cndmask_b32_e32 v12, v12, v180, vcc
	v_cndmask_b32_e32 v28, v28, v180, vcc
	v_cmp_gt_i32_e32 vcc, v34, v230
	v_or_b32_e32 v34, 24, v186
	s_nop 0
	v_cndmask_b32_e32 v13, v13, v180, vcc
	v_cndmask_b32_e32 v29, v29, v180, vcc
	v_cmp_gt_i32_e32 vcc, v34, v230
	v_or_b32_e32 v34, 25, v186
	s_nop 0
	v_cndmask_b32_e32 v14, v14, v180, vcc
	v_cndmask_b32_e32 v30, v30, v180, vcc
	v_cmp_gt_i32_e32 vcc, v34, v230
	v_or_b32_e32 v34, 26, v186
	s_nop 0
	v_cndmask_b32_e32 v15, v15, v180, vcc
	v_cndmask_b32_e32 v31, v31, v180, vcc
	v_cmp_gt_i32_e32 vcc, v34, v230
	v_or_b32_e32 v34, 27, v186
	s_nop 0
	v_cndmask_b32_e32 v16, v16, v180, vcc
	v_cndmask_b32_e32 v32, v32, v180, vcc
	v_cmp_gt_i32_e32 vcc, v34, v230
	s_nop 1
	v_cndmask_b32_e32 v17, v17, v180, vcc
	v_cndmask_b32_e32 v33, v33, v180, vcc
